# indexer search end-game: tokens off by exactly one (count 255 or 257) are finished by one max/min scan (tau = largest score below / next float above the smallest score at-or-above the candidate)
# speedup vs baseline: 1.0008x; 1.0008x over previous
.LBB0_1533:
	s_nop 1
	v_add_u32_dpp v7, v7, v7 quad_perm:[1,0,3,2] row_mask:0xf bank_mask:0xf bound_ctrl:1
	s_nop 1
	v_add_u32_dpp v7, v7, v7 quad_perm:[2,3,0,1] row_mask:0xf bank_mask:0xf bound_ctrl:1
	s_nop 1
	v_add_u32_dpp v7, v7, v7 row_half_mirror row_mask:0xf bank_mask:0xf bound_ctrl:1
	s_nop 1
	v_add_u32_dpp v7, v7, v7 row_mirror row_mask:0xf bank_mask:0xf bound_ctrl:1
	s_nop 1
	v_add_u32_dpp v7, v7, v7 row_bcast:15 row_mask:0xa bank_mask:0xf
	s_nop 0
	v_readlane_b32 s50, v7, 31
	v_readlane_b32 s51, v7, 63
	s_nop 1
	v_mov_b32_e32 v7, s51
	v_mov_b32_e32 v8, s50
	v_cndmask_b32_e64 v8, v7, v8, s[6:7]
	v_cmp_lt_i32_e64 s[82:83], s33, v8
	v_cmp_eq_u32_e64 s[84:85], s33, v8
	v_cvt_f32_i32_e32 v8, v8
	s_andn2_b64 s[84:85], s[84:85], s[72:73]
	s_nop 0
	v_cndmask_b32_e64 v6, v6, v0, s[84:85]
	s_or_b64 s[84:85], s[84:85], s[72:73]
	s_andn2_b64 s[86:87], s[82:83], s[84:85]
	s_or_b64 s[88:89], s[82:83], s[84:85]
	s_andn2_b64 s[88:89], exec, s[88:89]
	v_cndmask_b32_e64 v4, v4, v0, s[86:87]
	v_cndmask_b32_e64 v3, v3, v8, s[86:87]
	v_cndmask_b32_e64 v5, v5, v0, s[88:89]
	v_cndmask_b32_e64 v2, v2, v8, s[88:89]
	s_or_b64 s[78:79], s[78:79], s[86:87]
	s_or_b64 s[76:77], s[76:77], s[88:89]
	s_and_b64 s[90:91], s[78:79], s[76:77]
	v_sub_f32_e32 v9, v3, v2
	v_rcp_f32_e32 v9, v9
	v_add_f32_e32 v10, 0xc3800000, v3
	s_and_b32 s98, s58, 3
	s_cmp_lg_u32 s98, 3
	s_cselect_b64 vcc, -1, 0
	v_mul_f32_e32 v9, v10, v9
	v_max_f32_e32 v9, 0x3ca3d70a, v9
	v_min_f32_e32 v9, 0x3f7ae148, v9
	v_cndmask_b32_e32 v9, 0.5, v9, vcc
	v_sub_f32_e32 v10, v5, v4
	v_fma_f32 v10, v10, v9, v4
	v_mul_f32_e32 v11, 0.5, v5
	v_fmac_f32_e32 v11, 0.5, v4
	v_cmp_ngt_f32_e32 vcc, v10, v4
	v_cmp_nlt_f32_e64 s[98:99], v10, v5
	v_cmp_ngt_f32_e64 s[100:101], v11, v4
	s_or_b64 s[98:99], vcc, s[98:99]
	v_cmp_nlt_f32_e32 vcc, v11, v5
	s_nop 0
	v_cndmask_b32_e64 v10, v10, v11, s[98:99]
	s_or_b64 s[100:101], vcc, s[100:101]
	s_and_b64 s[100:101], s[100:101], s[98:99]
	s_and_b64 s[100:101], s[100:101], s[90:91]
	s_andn2_b64 s[100:101], s[100:101], s[84:85]
	v_cndmask_b32_e64 v11, -v1, v1, s[82:83]
	v_add_f32_e32 v11, v0, v11
	v_cndmask_b32_e64 v10, v11, v10, s[90:91]
	v_add_f32_e32 v11, v1, v1
	s_or_b64 s[98:99], s[90:91], s[84:85]
	s_andn2_b64 s[98:99], exec, s[98:99]
	v_cndmask_b32_e64 v1, v1, v11, s[98:99]
	v_cndmask_b32_e64 v6, v6, v4, s[100:101]
	s_or_b64 s[72:73], s[84:85], s[100:101]
	v_add_f32_e32 v9, 0xc3800000, v8
	v_cmp_eq_f32_e64 s[82:83], 1.0, |v9|
	s_andn2_b64 s[82:83], s[82:83], s[72:73]
	s_cmp_lg_u64 s[82:83], 0
	s_cbranch_scc1 .Lwalk0

.Lwalk0:
	v_cmp_gt_f32_e32 vcc, 0, v9
	s_and_b64 s[86:87], s[82:83], vcc
	s_andn2_b64 s[88:89], s[82:83], vcc
	s_cmp_lg_u64 s[86:87], 0
	s_cbranch_scc0 .Lwalk0_u
	v_mov_b32_e32 v100, 0xff800000
	v_mov_b32_e32 v101, 0xff800000
	v_cmp_lt_f32_e64 s[98:99], v201, v0
	v_cmp_lt_f32_e64 s[100:101], v209, v0
	v_cmp_lt_f32_e32 vcc, v200, v0
	v_cndmask_b32_e64 v104, v101, v201, s[98:99]
	v_cmp_lt_f32_e64 s[98:99], v202, v0
	v_max_f32_e32 v100, v100, v104
	v_cndmask_b32_e64 v105, v101, v209, s[100:101]
	v_cmp_lt_f32_e64 s[100:101], v112, v0
	v_max_f32_e32 v100, v100, v105
	v_cndmask_b32_e32 v104, v101, v200, vcc
	v_cmp_lt_f32_e32 vcc, v113, v0
	v_max_f32_e32 v100, v100, v104
	v_cndmask_b32_e64 v105, v101, v202, s[98:99]
	v_cmp_lt_f32_e64 s[98:99], v114, v0
	v_max_f32_e32 v100, v100, v105
	v_cndmask_b32_e64 v104, v101, v112, s[100:101]
	v_cmp_lt_f32_e64 s[100:101], v115, v0
	v_max_f32_e32 v100, v100, v104
	v_cndmask_b32_e32 v105, v101, v113, vcc
	v_cmp_lt_f32_e32 vcc, v116, v0
	v_max_f32_e32 v100, v100, v105
	v_cndmask_b32_e64 v104, v101, v114, s[98:99]
	v_cmp_lt_f32_e64 s[98:99], v117, v0
	v_max_f32_e32 v100, v100, v104
	v_cndmask_b32_e64 v105, v101, v115, s[100:101]
	v_cmp_lt_f32_e64 s[100:101], v118, v0
	v_max_f32_e32 v100, v100, v105
	v_cndmask_b32_e32 v104, v101, v116, vcc
	v_cmp_lt_f32_e32 vcc, v119, v0
	v_max_f32_e32 v100, v100, v104
	v_cndmask_b32_e64 v105, v101, v117, s[98:99]
	v_cmp_lt_f32_e64 s[98:99], v205, v0
	v_max_f32_e32 v100, v100, v105
	v_cndmask_b32_e64 v104, v101, v118, s[100:101]
	v_cmp_lt_f32_e64 s[100:101], v206, v0
	v_max_f32_e32 v100, v100, v104
	v_cndmask_b32_e32 v105, v101, v119, vcc
	v_cmp_lt_f32_e32 vcc, v207, v0
	v_max_f32_e32 v100, v100, v105
	v_cndmask_b32_e64 v104, v101, v205, s[98:99]
	v_cmp_lt_f32_e64 s[98:99], v208, v0
	v_max_f32_e32 v100, v100, v104
	v_cndmask_b32_e64 v105, v101, v206, s[100:101]
	v_cmp_lt_f32_e64 s[100:101], v210, v0
	v_max_f32_e32 v100, v100, v105
	v_cndmask_b32_e32 v104, v101, v207, vcc
	v_cmp_lt_f32_e32 vcc, v212, v0
	v_max_f32_e32 v100, v100, v104
	v_cndmask_b32_e64 v105, v101, v208, s[98:99]
	v_cmp_lt_f32_e64 s[98:99], v214, v0
	v_max_f32_e32 v100, v100, v105
	v_cndmask_b32_e64 v104, v101, v210, s[100:101]
	v_cmp_lt_f32_e64 s[100:101], v217, v0
	v_max_f32_e32 v100, v100, v104
	v_cndmask_b32_e32 v105, v101, v212, vcc
	v_cmp_lt_f32_e32 vcc, v211, v0
	v_max_f32_e32 v100, v100, v105
	v_cndmask_b32_e64 v104, v101, v214, s[98:99]
	v_cmp_lt_f32_e64 s[98:99], v213, v0
	v_max_f32_e32 v100, v100, v104
	v_cndmask_b32_e64 v105, v101, v217, s[100:101]
	v_cmp_lt_f32_e64 s[100:101], v216, v0
	v_max_f32_e32 v100, v100, v105
	v_cndmask_b32_e32 v104, v101, v211, vcc
	v_cmp_lt_f32_e32 vcc, v218, v0
	v_max_f32_e32 v100, v100, v104
	v_cndmask_b32_e64 v105, v101, v213, s[98:99]
	v_cmp_lt_f32_e64 s[98:99], v227, v0
	v_max_f32_e32 v100, v100, v105
	v_cndmask_b32_e64 v104, v101, v216, s[100:101]
	v_cmp_lt_f32_e64 s[100:101], v229, v0
	v_max_f32_e32 v100, v100, v104
	v_cndmask_b32_e32 v105, v101, v218, vcc
	v_cmp_lt_f32_e32 vcc, v231, v0
	v_max_f32_e32 v100, v100, v105
	v_cndmask_b32_e64 v104, v101, v227, s[98:99]
	v_cmp_lt_f32_e64 s[98:99], v233, v0
	v_max_f32_e32 v100, v100, v104
	v_cndmask_b32_e64 v105, v101, v229, s[100:101]
	v_cmp_lt_f32_e64 s[100:101], v228, v0
	v_max_f32_e32 v100, v100, v105
	v_cndmask_b32_e32 v104, v101, v231, vcc
	v_cmp_lt_f32_e32 vcc, v230, v0
	v_max_f32_e32 v100, v100, v104
	v_cndmask_b32_e64 v105, v101, v233, s[98:99]
	v_cmp_lt_f32_e64 s[98:99], v232, v0
	v_max_f32_e32 v100, v100, v105
	v_cndmask_b32_e64 v104, v101, v228, s[100:101]
	v_cmp_lt_f32_e64 s[100:101], v234, v0
	v_max_f32_e32 v100, v100, v104
	v_cndmask_b32_e32 v105, v101, v230, vcc
	v_cmp_lt_f32_e32 vcc, v243, v0
	v_max_f32_e32 v100, v100, v105
	v_cndmask_b32_e64 v104, v101, v232, s[98:99]
	v_cmp_lt_f32_e64 s[98:99], v245, v0
	v_max_f32_e32 v100, v100, v104
	v_cndmask_b32_e64 v105, v101, v234, s[100:101]
	v_cmp_lt_f32_e64 s[100:101], v247, v0
	v_max_f32_e32 v100, v100, v105
	v_cndmask_b32_e32 v104, v101, v243, vcc
	v_cmp_lt_f32_e32 vcc, v249, v0
	v_max_f32_e32 v100, v100, v104
	v_cndmask_b32_e64 v105, v101, v245, s[98:99]
	v_cmp_lt_f32_e64 s[98:99], v244, v0
	v_max_f32_e32 v100, v100, v105
	v_cndmask_b32_e64 v104, v101, v247, s[100:101]
	v_cmp_lt_f32_e64 s[100:101], v246, v0
	v_max_f32_e32 v100, v100, v104
	v_cndmask_b32_e32 v105, v101, v249, vcc
	v_cmp_lt_f32_e32 vcc, v248, v0
	v_max_f32_e32 v100, v100, v105
	v_cndmask_b32_e64 v104, v101, v244, s[98:99]
	v_cmp_lt_f32_e64 s[98:99], v250, v0
	v_max_f32_e32 v100, v100, v104
	v_cndmask_b32_e64 v105, v101, v246, s[100:101]
	v_cmp_lt_f32_e64 s[100:101], v219, v0
	v_max_f32_e32 v100, v100, v105
	v_cndmask_b32_e32 v104, v101, v248, vcc
	v_cmp_lt_f32_e32 vcc, v221, v0
	v_max_f32_e32 v100, v100, v104
	v_cndmask_b32_e64 v105, v101, v250, s[98:99]
	v_cmp_lt_f32_e64 s[98:99], v223, v0
	v_max_f32_e32 v100, v100, v105
	v_cndmask_b32_e64 v104, v101, v219, s[100:101]
	v_cmp_lt_f32_e64 s[100:101], v225, v0
	v_max_f32_e32 v100, v100, v104
	v_cndmask_b32_e32 v105, v101, v221, vcc
	v_cmp_lt_f32_e32 vcc, v220, v0
	v_max_f32_e32 v100, v100, v105
	v_cndmask_b32_e64 v104, v101, v223, s[98:99]
	v_cmp_lt_f32_e64 s[98:99], v222, v0
	v_max_f32_e32 v100, v100, v104
	v_cndmask_b32_e64 v105, v101, v225, s[100:101]
	v_cmp_lt_f32_e64 s[100:101], v224, v0
	v_max_f32_e32 v100, v100, v105
	v_cndmask_b32_e32 v104, v101, v220, vcc
	v_cmp_lt_f32_e32 vcc, v226, v0
	v_max_f32_e32 v100, v100, v104
	v_cndmask_b32_e64 v105, v101, v222, s[98:99]
	v_cmp_lt_f32_e64 s[98:99], v235, v0
	v_max_f32_e32 v100, v100, v105
	v_cndmask_b32_e64 v104, v101, v224, s[100:101]
	v_cmp_lt_f32_e64 s[100:101], v237, v0
	v_max_f32_e32 v100, v100, v104
	v_cndmask_b32_e32 v105, v101, v226, vcc
	v_cmp_lt_f32_e32 vcc, v239, v0
	v_max_f32_e32 v100, v100, v105
	v_cndmask_b32_e64 v104, v101, v235, s[98:99]
	v_cmp_lt_f32_e64 s[98:99], v241, v0
	v_max_f32_e32 v100, v100, v104
	v_cndmask_b32_e64 v105, v101, v237, s[100:101]
	v_cmp_lt_f32_e64 s[100:101], v236, v0
	v_max_f32_e32 v100, v100, v105
	v_cndmask_b32_e32 v104, v101, v239, vcc
	v_cmp_lt_f32_e32 vcc, v238, v0
	v_max_f32_e32 v100, v100, v104
	v_cndmask_b32_e64 v105, v101, v241, s[98:99]
	v_cmp_lt_f32_e64 s[98:99], v240, v0
	v_max_f32_e32 v100, v100, v105
	v_cndmask_b32_e64 v104, v101, v236, s[100:101]
	v_cmp_lt_f32_e64 s[100:101], v242, v0
	v_max_f32_e32 v100, v100, v104
	v_cndmask_b32_e32 v105, v101, v238, vcc
	v_cmp_lt_f32_e32 vcc, v251, v0
	v_max_f32_e32 v100, v100, v105
	v_cndmask_b32_e64 v104, v101, v240, s[98:99]
	v_cmp_lt_f32_e64 s[98:99], v253, v0
	v_max_f32_e32 v100, v100, v104
	v_cndmask_b32_e64 v105, v101, v242, s[100:101]
	v_cmp_lt_f32_e64 s[100:101], v133, v0
	v_max_f32_e32 v100, v100, v105
	v_cndmask_b32_e32 v104, v101, v251, vcc
	v_cmp_lt_f32_e32 vcc, v80, v0
	v_max_f32_e32 v100, v100, v104
	v_cndmask_b32_e64 v105, v101, v253, s[98:99]
	v_cmp_lt_f32_e64 s[98:99], v252, v0
	v_max_f32_e32 v100, v100, v105
	v_cndmask_b32_e64 v104, v101, v133, s[100:101]
	v_cmp_lt_f32_e64 s[100:101], v215, v0
	v_max_f32_e32 v100, v100, v104
	v_cndmask_b32_e32 v105, v101, v80, vcc
	v_cmp_lt_f32_e32 vcc, v84, v0
	v_max_f32_e32 v100, v100, v105
	v_cndmask_b32_e64 v104, v101, v252, s[98:99]
	v_cmp_lt_f32_e64 s[98:99], v16, v0
	v_max_f32_e32 v100, v100, v104
	v_cndmask_b32_e64 v105, v101, v215, s[100:101]
	v_max_f32_e32 v100, v100, v105
	v_cndmask_b32_e32 v104, v101, v84, vcc
	v_max_f32_e32 v100, v100, v104
	v_cndmask_b32_e64 v105, v101, v16, s[98:99]
	v_max_f32_e32 v100, v100, v105
	s_nop 1
	v_max_f32_dpp v100, v100, v100 quad_perm:[1,0,3,2] row_mask:0xf bank_mask:0xf
	s_nop 1
	v_max_f32_dpp v100, v100, v100 quad_perm:[2,3,0,1] row_mask:0xf bank_mask:0xf
	s_nop 1
	v_max_f32_dpp v100, v100, v100 row_half_mirror row_mask:0xf bank_mask:0xf
	s_nop 1
	v_max_f32_dpp v100, v100, v100 row_mirror row_mask:0xf bank_mask:0xf
	s_nop 1
	v_max_f32_dpp v100, v100, v100 row_bcast:15 row_mask:0xa bank_mask:0xf
	s_nop 0
	v_readlane_b32 s98, v100, 31
	v_readlane_b32 s99, v100, 63
	s_nop 1
	v_mov_b32_e32 v102, s99
	v_mov_b32_e32 v103, s98
	v_cndmask_b32_e64 v102, v102, v103, s[6:7]
	v_cndmask_b32_e64 v6, v6, v102, s[86:87]
.Lwalk0_u:
	s_cmp_lg_u64 s[88:89], 0
	s_cbranch_scc0 .Lwalk0_e
	v_mov_b32_e32 v100, 0x7f800000
	v_mov_b32_e32 v101, 0x7f800000
	v_cmp_ge_f32_e64 s[98:99], v201, v0
	v_cmp_ge_f32_e64 s[100:101], v209, v0
	v_cmp_ge_f32_e32 vcc, v200, v0
	v_cndmask_b32_e64 v104, v101, v201, s[98:99]
	v_cmp_ge_f32_e64 s[98:99], v202, v0
	v_min_f32_e32 v100, v100, v104
	v_cndmask_b32_e64 v105, v101, v209, s[100:101]
	v_cmp_ge_f32_e64 s[100:101], v112, v0
	v_min_f32_e32 v100, v100, v105
	v_cndmask_b32_e32 v104, v101, v200, vcc
	v_cmp_ge_f32_e32 vcc, v113, v0
	v_min_f32_e32 v100, v100, v104
	v_cndmask_b32_e64 v105, v101, v202, s[98:99]
	v_cmp_ge_f32_e64 s[98:99], v114, v0
	v_min_f32_e32 v100, v100, v105
	v_cndmask_b32_e64 v104, v101, v112, s[100:101]
	v_cmp_ge_f32_e64 s[100:101], v115, v0
	v_min_f32_e32 v100, v100, v104
	v_cndmask_b32_e32 v105, v101, v113, vcc
	v_cmp_ge_f32_e32 vcc, v116, v0
	v_min_f32_e32 v100, v100, v105
	v_cndmask_b32_e64 v104, v101, v114, s[98:99]
	v_cmp_ge_f32_e64 s[98:99], v117, v0
	v_min_f32_e32 v100, v100, v104
	v_cndmask_b32_e64 v105, v101, v115, s[100:101]
	v_cmp_ge_f32_e64 s[100:101], v118, v0
	v_min_f32_e32 v100, v100, v105
	v_cndmask_b32_e32 v104, v101, v116, vcc
	v_cmp_ge_f32_e32 vcc, v119, v0
	v_min_f32_e32 v100, v100, v104
	v_cndmask_b32_e64 v105, v101, v117, s[98:99]
	v_cmp_ge_f32_e64 s[98:99], v205, v0
	v_min_f32_e32 v100, v100, v105
	v_cndmask_b32_e64 v104, v101, v118, s[100:101]
	v_cmp_ge_f32_e64 s[100:101], v206, v0
	v_min_f32_e32 v100, v100, v104
	v_cndmask_b32_e32 v105, v101, v119, vcc
	v_cmp_ge_f32_e32 vcc, v207, v0
	v_min_f32_e32 v100, v100, v105
	v_cndmask_b32_e64 v104, v101, v205, s[98:99]
	v_cmp_ge_f32_e64 s[98:99], v208, v0
	v_min_f32_e32 v100, v100, v104
	v_cndmask_b32_e64 v105, v101, v206, s[100:101]
	v_cmp_ge_f32_e64 s[100:101], v210, v0
	v_min_f32_e32 v100, v100, v105
	v_cndmask_b32_e32 v104, v101, v207, vcc
	v_cmp_ge_f32_e32 vcc, v212, v0
	v_min_f32_e32 v100, v100, v104
	v_cndmask_b32_e64 v105, v101, v208, s[98:99]
	v_cmp_ge_f32_e64 s[98:99], v214, v0
	v_min_f32_e32 v100, v100, v105
	v_cndmask_b32_e64 v104, v101, v210, s[100:101]
	v_cmp_ge_f32_e64 s[100:101], v217, v0
	v_min_f32_e32 v100, v100, v104
	v_cndmask_b32_e32 v105, v101, v212, vcc
	v_cmp_ge_f32_e32 vcc, v211, v0
	v_min_f32_e32 v100, v100, v105
	v_cndmask_b32_e64 v104, v101, v214, s[98:99]
	v_cmp_ge_f32_e64 s[98:99], v213, v0
	v_min_f32_e32 v100, v100, v104
	v_cndmask_b32_e64 v105, v101, v217, s[100:101]
	v_cmp_ge_f32_e64 s[100:101], v216, v0
	v_min_f32_e32 v100, v100, v105
	v_cndmask_b32_e32 v104, v101, v211, vcc
	v_cmp_ge_f32_e32 vcc, v218, v0
	v_min_f32_e32 v100, v100, v104
	v_cndmask_b32_e64 v105, v101, v213, s[98:99]
	v_cmp_ge_f32_e64 s[98:99], v227, v0
	v_min_f32_e32 v100, v100, v105
	v_cndmask_b32_e64 v104, v101, v216, s[100:101]
	v_cmp_ge_f32_e64 s[100:101], v229, v0
	v_min_f32_e32 v100, v100, v104
	v_cndmask_b32_e32 v105, v101, v218, vcc
	v_cmp_ge_f32_e32 vcc, v231, v0
	v_min_f32_e32 v100, v100, v105
	v_cndmask_b32_e64 v104, v101, v227, s[98:99]
	v_cmp_ge_f32_e64 s[98:99], v233, v0
	v_min_f32_e32 v100, v100, v104
	v_cndmask_b32_e64 v105, v101, v229, s[100:101]
	v_cmp_ge_f32_e64 s[100:101], v228, v0
	v_min_f32_e32 v100, v100, v105
	v_cndmask_b32_e32 v104, v101, v231, vcc
	v_cmp_ge_f32_e32 vcc, v230, v0
	v_min_f32_e32 v100, v100, v104
	v_cndmask_b32_e64 v105, v101, v233, s[98:99]
	v_cmp_ge_f32_e64 s[98:99], v232, v0
	v_min_f32_e32 v100, v100, v105
	v_cndmask_b32_e64 v104, v101, v228, s[100:101]
	v_cmp_ge_f32_e64 s[100:101], v234, v0
	v_min_f32_e32 v100, v100, v104
	v_cndmask_b32_e32 v105, v101, v230, vcc
	v_cmp_ge_f32_e32 vcc, v243, v0
	v_min_f32_e32 v100, v100, v105
	v_cndmask_b32_e64 v104, v101, v232, s[98:99]
	v_cmp_ge_f32_e64 s[98:99], v245, v0
	v_min_f32_e32 v100, v100, v104
	v_cndmask_b32_e64 v105, v101, v234, s[100:101]
	v_cmp_ge_f32_e64 s[100:101], v247, v0
	v_min_f32_e32 v100, v100, v105
	v_cndmask_b32_e32 v104, v101, v243, vcc
	v_cmp_ge_f32_e32 vcc, v249, v0
	v_min_f32_e32 v100, v100, v104
	v_cndmask_b32_e64 v105, v101, v245, s[98:99]
	v_cmp_ge_f32_e64 s[98:99], v244, v0
	v_min_f32_e32 v100, v100, v105
	v_cndmask_b32_e64 v104, v101, v247, s[100:101]
	v_cmp_ge_f32_e64 s[100:101], v246, v0
	v_min_f32_e32 v100, v100, v104
	v_cndmask_b32_e32 v105, v101, v249, vcc
	v_cmp_ge_f32_e32 vcc, v248, v0
	v_min_f32_e32 v100, v100, v105
	v_cndmask_b32_e64 v104, v101, v244, s[98:99]
	v_cmp_ge_f32_e64 s[98:99], v250, v0
	v_min_f32_e32 v100, v100, v104
	v_cndmask_b32_e64 v105, v101, v246, s[100:101]
	v_cmp_ge_f32_e64 s[100:101], v219, v0
	v_min_f32_e32 v100, v100, v105
	v_cndmask_b32_e32 v104, v101, v248, vcc
	v_cmp_ge_f32_e32 vcc, v221, v0
	v_min_f32_e32 v100, v100, v104
	v_cndmask_b32_e64 v105, v101, v250, s[98:99]
	v_cmp_ge_f32_e64 s[98:99], v223, v0
	v_min_f32_e32 v100, v100, v105
	v_cndmask_b32_e64 v104, v101, v219, s[100:101]
	v_cmp_ge_f32_e64 s[100:101], v225, v0
	v_min_f32_e32 v100, v100, v104
	v_cndmask_b32_e32 v105, v101, v221, vcc
	v_cmp_ge_f32_e32 vcc, v220, v0
	v_min_f32_e32 v100, v100, v105
	v_cndmask_b32_e64 v104, v101, v223, s[98:99]
	v_cmp_ge_f32_e64 s[98:99], v222, v0
	v_min_f32_e32 v100, v100, v104
	v_cndmask_b32_e64 v105, v101, v225, s[100:101]
	v_cmp_ge_f32_e64 s[100:101], v224, v0
	v_min_f32_e32 v100, v100, v105
	v_cndmask_b32_e32 v104, v101, v220, vcc
	v_cmp_ge_f32_e32 vcc, v226, v0
	v_min_f32_e32 v100, v100, v104
	v_cndmask_b32_e64 v105, v101, v222, s[98:99]
	v_cmp_ge_f32_e64 s[98:99], v235, v0
	v_min_f32_e32 v100, v100, v105
	v_cndmask_b32_e64 v104, v101, v224, s[100:101]
	v_cmp_ge_f32_e64 s[100:101], v237, v0
	v_min_f32_e32 v100, v100, v104
	v_cndmask_b32_e32 v105, v101, v226, vcc
	v_cmp_ge_f32_e32 vcc, v239, v0
	v_min_f32_e32 v100, v100, v105
	v_cndmask_b32_e64 v104, v101, v235, s[98:99]
	v_cmp_ge_f32_e64 s[98:99], v241, v0
	v_min_f32_e32 v100, v100, v104
	v_cndmask_b32_e64 v105, v101, v237, s[100:101]
	v_cmp_ge_f32_e64 s[100:101], v236, v0
	v_min_f32_e32 v100, v100, v105
	v_cndmask_b32_e32 v104, v101, v239, vcc
	v_cmp_ge_f32_e32 vcc, v238, v0
	v_min_f32_e32 v100, v100, v104
	v_cndmask_b32_e64 v105, v101, v241, s[98:99]
	v_cmp_ge_f32_e64 s[98:99], v240, v0
	v_min_f32_e32 v100, v100, v105
	v_cndmask_b32_e64 v104, v101, v236, s[100:101]
	v_cmp_ge_f32_e64 s[100:101], v242, v0
	v_min_f32_e32 v100, v100, v104
	v_cndmask_b32_e32 v105, v101, v238, vcc
	v_cmp_ge_f32_e32 vcc, v251, v0
	v_min_f32_e32 v100, v100, v105
	v_cndmask_b32_e64 v104, v101, v240, s[98:99]
	v_cmp_ge_f32_e64 s[98:99], v253, v0
	v_min_f32_e32 v100, v100, v104
	v_cndmask_b32_e64 v105, v101, v242, s[100:101]
	v_cmp_ge_f32_e64 s[100:101], v133, v0
	v_min_f32_e32 v100, v100, v105
	v_cndmask_b32_e32 v104, v101, v251, vcc
	v_cmp_ge_f32_e32 vcc, v80, v0
	v_min_f32_e32 v100, v100, v104
	v_cndmask_b32_e64 v105, v101, v253, s[98:99]
	v_cmp_ge_f32_e64 s[98:99], v252, v0
	v_min_f32_e32 v100, v100, v105
	v_cndmask_b32_e64 v104, v101, v133, s[100:101]
	v_cmp_ge_f32_e64 s[100:101], v215, v0
	v_min_f32_e32 v100, v100, v104
	v_cndmask_b32_e32 v105, v101, v80, vcc
	v_cmp_ge_f32_e32 vcc, v84, v0
	v_min_f32_e32 v100, v100, v105
	v_cndmask_b32_e64 v104, v101, v252, s[98:99]
	v_cmp_ge_f32_e64 s[98:99], v16, v0
	v_min_f32_e32 v100, v100, v104
	v_cndmask_b32_e64 v105, v101, v215, s[100:101]
	v_min_f32_e32 v100, v100, v105
	v_cndmask_b32_e32 v104, v101, v84, vcc
	v_min_f32_e32 v100, v100, v104
	v_cndmask_b32_e64 v105, v101, v16, s[98:99]
	v_min_f32_e32 v100, v100, v105
	s_nop 1
	v_min_f32_dpp v100, v100, v100 quad_perm:[1,0,3,2] row_mask:0xf bank_mask:0xf
	s_nop 1
	v_min_f32_dpp v100, v100, v100 quad_perm:[2,3,0,1] row_mask:0xf bank_mask:0xf
	s_nop 1
	v_min_f32_dpp v100, v100, v100 row_half_mirror row_mask:0xf bank_mask:0xf
	s_nop 1
	v_min_f32_dpp v100, v100, v100 row_mirror row_mask:0xf bank_mask:0xf
	s_nop 1
	v_min_f32_dpp v100, v100, v100 row_bcast:15 row_mask:0xa bank_mask:0xf
	s_nop 0
	v_readlane_b32 s98, v100, 31
	v_readlane_b32 s99, v100, 63
	s_nop 1
	v_mov_b32_e32 v102, s99
	v_mov_b32_e32 v103, s98
	v_cndmask_b32_e64 v102, v102, v103, s[6:7]
	v_add_f32_e32 v102, 0, v102
	v_ashrrev_i32_e32 v103, 31, v102
	v_or_b32_e32 v103, 1, v103
	v_add_u32_e32 v103, v102, v103
	v_cmp_lg_f32_e32 vcc, 0, v102
	s_and_b64 s[88:89], s[88:89], vcc
	v_cndmask_b32_e64 v6, v6, v103, s[88:89]
.Lwalk0_e:
	s_or_b64 s[82:83], s[86:87], s[88:89]
	s_or_b64 s[72:73], s[72:73], s[82:83]
	s_branch .Lwalkret0

.LBB0_2136:
	s_nop 1
	v_add_u32_dpp v7, v7, v7 quad_perm:[1,0,3,2] row_mask:0xf bank_mask:0xf bound_ctrl:1
	s_nop 1
	v_add_u32_dpp v7, v7, v7 quad_perm:[2,3,0,1] row_mask:0xf bank_mask:0xf bound_ctrl:1
	s_nop 1
	v_add_u32_dpp v7, v7, v7 row_half_mirror row_mask:0xf bank_mask:0xf bound_ctrl:1
	s_nop 1
	v_add_u32_dpp v7, v7, v7 row_mirror row_mask:0xf bank_mask:0xf bound_ctrl:1
	s_nop 1
	v_add_u32_dpp v7, v7, v7 row_bcast:15 row_mask:0xa bank_mask:0xf
	s_nop 0
	v_readlane_b32 s0, v7, 31
	v_readlane_b32 s1, v7, 63
	s_nop 1
	v_mov_b32_e32 v7, s1
	v_mov_b32_e32 v8, s0
	v_cndmask_b32_e64 v8, v7, v8, s[8:9]
	v_cmp_lt_i32_e64 s[82:83], s33, v8
	v_cmp_eq_u32_e64 s[84:85], s33, v8
	v_cvt_f32_i32_e32 v8, v8
	s_andn2_b64 s[84:85], s[84:85], s[74:75]
	s_nop 0
	v_cndmask_b32_e64 v6, v6, v0, s[84:85]
	s_or_b64 s[84:85], s[84:85], s[74:75]
	s_andn2_b64 s[86:87], s[82:83], s[84:85]
	s_or_b64 s[88:89], s[82:83], s[84:85]
	s_andn2_b64 s[88:89], exec, s[88:89]
	v_cndmask_b32_e64 v4, v4, v0, s[86:87]
	v_cndmask_b32_e64 v3, v3, v8, s[86:87]
	v_cndmask_b32_e64 v5, v5, v0, s[88:89]
	v_cndmask_b32_e64 v2, v2, v8, s[88:89]
	s_or_b64 s[80:81], s[80:81], s[86:87]
	s_or_b64 s[78:79], s[78:79], s[88:89]
	s_and_b64 s[90:91], s[80:81], s[78:79]
	v_sub_f32_e32 v9, v3, v2
	v_rcp_f32_e32 v9, v9
	v_add_f32_e32 v10, 0xc3800000, v3
	s_and_b32 s98, s60, 3
	s_cmp_lg_u32 s98, 3
	s_cselect_b64 vcc, -1, 0
	v_mul_f32_e32 v9, v10, v9
	v_max_f32_e32 v9, 0x3ca3d70a, v9
	v_min_f32_e32 v9, 0x3f7ae148, v9
	v_cndmask_b32_e32 v9, 0.5, v9, vcc
	v_sub_f32_e32 v10, v5, v4
	v_fma_f32 v10, v10, v9, v4
	v_mul_f32_e32 v11, 0.5, v5
	v_fmac_f32_e32 v11, 0.5, v4
	v_cmp_ngt_f32_e32 vcc, v10, v4
	v_cmp_nlt_f32_e64 s[98:99], v10, v5
	v_cmp_ngt_f32_e64 s[100:101], v11, v4
	s_or_b64 s[98:99], vcc, s[98:99]
	v_cmp_nlt_f32_e32 vcc, v11, v5
	s_nop 0
	v_cndmask_b32_e64 v10, v10, v11, s[98:99]
	s_or_b64 s[100:101], vcc, s[100:101]
	s_and_b64 s[100:101], s[100:101], s[98:99]
	s_and_b64 s[100:101], s[100:101], s[90:91]
	s_andn2_b64 s[100:101], s[100:101], s[84:85]
	v_cndmask_b32_e64 v11, -v1, v1, s[82:83]
	v_add_f32_e32 v11, v0, v11
	v_cndmask_b32_e64 v10, v11, v10, s[90:91]
	v_add_f32_e32 v11, v1, v1
	s_or_b64 s[98:99], s[90:91], s[84:85]
	s_andn2_b64 s[98:99], exec, s[98:99]
	v_cndmask_b32_e64 v1, v1, v11, s[98:99]
	v_cndmask_b32_e64 v6, v6, v4, s[100:101]
	s_or_b64 s[74:75], s[84:85], s[100:101]
	v_add_f32_e32 v9, 0xc3800000, v8
	v_cmp_eq_f32_e64 s[82:83], 1.0, |v9|
	s_andn2_b64 s[82:83], s[82:83], s[74:75]
	s_cmp_lg_u64 s[82:83], 0
	s_cbranch_scc1 .Lwalk1

.Lwalk1:
	v_cmp_gt_f32_e32 vcc, 0, v9
	s_and_b64 s[86:87], s[82:83], vcc
	s_andn2_b64 s[88:89], s[82:83], vcc
	s_cmp_lg_u64 s[86:87], 0
	s_cbranch_scc0 .Lwalk1_u
	v_mov_b32_e32 v100, 0xff800000
	v_mov_b32_e32 v101, 0xff800000
	v_cmp_lt_f32_e64 s[98:99], v201, v0
	v_cmp_lt_f32_e64 s[100:101], v209, v0
	v_cmp_lt_f32_e32 vcc, v200, v0
	v_cndmask_b32_e64 v104, v101, v201, s[98:99]
	v_cmp_lt_f32_e64 s[98:99], v202, v0
	v_max_f32_e32 v100, v100, v104
	v_cndmask_b32_e64 v105, v101, v209, s[100:101]
	v_cmp_lt_f32_e64 s[100:101], v112, v0
	v_max_f32_e32 v100, v100, v105
	v_cndmask_b32_e32 v104, v101, v200, vcc
	v_cmp_lt_f32_e32 vcc, v113, v0
	v_max_f32_e32 v100, v100, v104
	v_cndmask_b32_e64 v105, v101, v202, s[98:99]
	v_cmp_lt_f32_e64 s[98:99], v114, v0
	v_max_f32_e32 v100, v100, v105
	v_cndmask_b32_e64 v104, v101, v112, s[100:101]
	v_cmp_lt_f32_e64 s[100:101], v115, v0
	v_max_f32_e32 v100, v100, v104
	v_cndmask_b32_e32 v105, v101, v113, vcc
	v_cmp_lt_f32_e32 vcc, v116, v0
	v_max_f32_e32 v100, v100, v105
	v_cndmask_b32_e64 v104, v101, v114, s[98:99]
	v_cmp_lt_f32_e64 s[98:99], v117, v0
	v_max_f32_e32 v100, v100, v104
	v_cndmask_b32_e64 v105, v101, v115, s[100:101]
	v_cmp_lt_f32_e64 s[100:101], v118, v0
	v_max_f32_e32 v100, v100, v105
	v_cndmask_b32_e32 v104, v101, v116, vcc
	v_cmp_lt_f32_e32 vcc, v119, v0
	v_max_f32_e32 v100, v100, v104
	v_cndmask_b32_e64 v105, v101, v117, s[98:99]
	v_cmp_lt_f32_e64 s[98:99], v205, v0
	v_max_f32_e32 v100, v100, v105
	v_cndmask_b32_e64 v104, v101, v118, s[100:101]
	v_cmp_lt_f32_e64 s[100:101], v206, v0
	v_max_f32_e32 v100, v100, v104
	v_cndmask_b32_e32 v105, v101, v119, vcc
	v_cmp_lt_f32_e32 vcc, v207, v0
	v_max_f32_e32 v100, v100, v105
	v_cndmask_b32_e64 v104, v101, v205, s[98:99]
	v_cmp_lt_f32_e64 s[98:99], v208, v0
	v_max_f32_e32 v100, v100, v104
	v_cndmask_b32_e64 v105, v101, v206, s[100:101]
	v_cmp_lt_f32_e64 s[100:101], v210, v0
	v_max_f32_e32 v100, v100, v105
	v_cndmask_b32_e32 v104, v101, v207, vcc
	v_cmp_lt_f32_e32 vcc, v212, v0
	v_max_f32_e32 v100, v100, v104
	v_cndmask_b32_e64 v105, v101, v208, s[98:99]
	v_cmp_lt_f32_e64 s[98:99], v214, v0
	v_max_f32_e32 v100, v100, v105
	v_cndmask_b32_e64 v104, v101, v210, s[100:101]
	v_cmp_lt_f32_e64 s[100:101], v217, v0
	v_max_f32_e32 v100, v100, v104
	v_cndmask_b32_e32 v105, v101, v212, vcc
	v_cmp_lt_f32_e32 vcc, v211, v0
	v_max_f32_e32 v100, v100, v105
	v_cndmask_b32_e64 v104, v101, v214, s[98:99]
	v_cmp_lt_f32_e64 s[98:99], v213, v0
	v_max_f32_e32 v100, v100, v104
	v_cndmask_b32_e64 v105, v101, v217, s[100:101]
	v_cmp_lt_f32_e64 s[100:101], v216, v0
	v_max_f32_e32 v100, v100, v105
	v_cndmask_b32_e32 v104, v101, v211, vcc
	v_cmp_lt_f32_e32 vcc, v218, v0
	v_max_f32_e32 v100, v100, v104
	v_cndmask_b32_e64 v105, v101, v213, s[98:99]
	v_cmp_lt_f32_e64 s[98:99], v227, v0
	v_max_f32_e32 v100, v100, v105
	v_cndmask_b32_e64 v104, v101, v216, s[100:101]
	v_cmp_lt_f32_e64 s[100:101], v229, v0
	v_max_f32_e32 v100, v100, v104
	v_cndmask_b32_e32 v105, v101, v218, vcc
	v_cmp_lt_f32_e32 vcc, v231, v0
	v_max_f32_e32 v100, v100, v105
	v_cndmask_b32_e64 v104, v101, v227, s[98:99]
	v_cmp_lt_f32_e64 s[98:99], v233, v0
	v_max_f32_e32 v100, v100, v104
	v_cndmask_b32_e64 v105, v101, v229, s[100:101]
	v_cmp_lt_f32_e64 s[100:101], v228, v0
	v_max_f32_e32 v100, v100, v105
	v_cndmask_b32_e32 v104, v101, v231, vcc
	v_cmp_lt_f32_e32 vcc, v230, v0
	v_max_f32_e32 v100, v100, v104
	v_cndmask_b32_e64 v105, v101, v233, s[98:99]
	v_cmp_lt_f32_e64 s[98:99], v232, v0
	v_max_f32_e32 v100, v100, v105
	v_cndmask_b32_e64 v104, v101, v228, s[100:101]
	v_cmp_lt_f32_e64 s[100:101], v234, v0
	v_max_f32_e32 v100, v100, v104
	v_cndmask_b32_e32 v105, v101, v230, vcc
	v_cmp_lt_f32_e32 vcc, v243, v0
	v_max_f32_e32 v100, v100, v105
	v_cndmask_b32_e64 v104, v101, v232, s[98:99]
	v_cmp_lt_f32_e64 s[98:99], v245, v0
	v_max_f32_e32 v100, v100, v104
	v_cndmask_b32_e64 v105, v101, v234, s[100:101]
	v_cmp_lt_f32_e64 s[100:101], v247, v0
	v_max_f32_e32 v100, v100, v105
	v_cndmask_b32_e32 v104, v101, v243, vcc
	v_cmp_lt_f32_e32 vcc, v249, v0
	v_max_f32_e32 v100, v100, v104
	v_cndmask_b32_e64 v105, v101, v245, s[98:99]
	v_cmp_lt_f32_e64 s[98:99], v244, v0
	v_max_f32_e32 v100, v100, v105
	v_cndmask_b32_e64 v104, v101, v247, s[100:101]
	v_cmp_lt_f32_e64 s[100:101], v246, v0
	v_max_f32_e32 v100, v100, v104
	v_cndmask_b32_e32 v105, v101, v249, vcc
	v_cmp_lt_f32_e32 vcc, v248, v0
	v_max_f32_e32 v100, v100, v105
	v_cndmask_b32_e64 v104, v101, v244, s[98:99]
	v_cmp_lt_f32_e64 s[98:99], v250, v0
	v_max_f32_e32 v100, v100, v104
	v_cndmask_b32_e64 v105, v101, v246, s[100:101]
	v_cmp_lt_f32_e64 s[100:101], v219, v0
	v_max_f32_e32 v100, v100, v105
	v_cndmask_b32_e32 v104, v101, v248, vcc
	v_cmp_lt_f32_e32 vcc, v221, v0
	v_max_f32_e32 v100, v100, v104
	v_cndmask_b32_e64 v105, v101, v250, s[98:99]
	v_cmp_lt_f32_e64 s[98:99], v223, v0
	v_max_f32_e32 v100, v100, v105
	v_cndmask_b32_e64 v104, v101, v219, s[100:101]
	v_cmp_lt_f32_e64 s[100:101], v225, v0
	v_max_f32_e32 v100, v100, v104
	v_cndmask_b32_e32 v105, v101, v221, vcc
	v_cmp_lt_f32_e32 vcc, v220, v0
	v_max_f32_e32 v100, v100, v105
	v_cndmask_b32_e64 v104, v101, v223, s[98:99]
	v_cmp_lt_f32_e64 s[98:99], v222, v0
	v_max_f32_e32 v100, v100, v104
	v_cndmask_b32_e64 v105, v101, v225, s[100:101]
	v_cmp_lt_f32_e64 s[100:101], v224, v0
	v_max_f32_e32 v100, v100, v105
	v_cndmask_b32_e32 v104, v101, v220, vcc
	v_cmp_lt_f32_e32 vcc, v226, v0
	v_max_f32_e32 v100, v100, v104
	v_cndmask_b32_e64 v105, v101, v222, s[98:99]
	v_cmp_lt_f32_e64 s[98:99], v235, v0
	v_max_f32_e32 v100, v100, v105
	v_cndmask_b32_e64 v104, v101, v224, s[100:101]
	v_cmp_lt_f32_e64 s[100:101], v237, v0
	v_max_f32_e32 v100, v100, v104
	v_cndmask_b32_e32 v105, v101, v226, vcc
	v_cmp_lt_f32_e32 vcc, v239, v0
	v_max_f32_e32 v100, v100, v105
	v_cndmask_b32_e64 v104, v101, v235, s[98:99]
	v_cmp_lt_f32_e64 s[98:99], v241, v0
	v_max_f32_e32 v100, v100, v104
	v_cndmask_b32_e64 v105, v101, v237, s[100:101]
	v_cmp_lt_f32_e64 s[100:101], v236, v0
	v_max_f32_e32 v100, v100, v105
	v_cndmask_b32_e32 v104, v101, v239, vcc
	v_cmp_lt_f32_e32 vcc, v238, v0
	v_max_f32_e32 v100, v100, v104
	v_cndmask_b32_e64 v105, v101, v241, s[98:99]
	v_cmp_lt_f32_e64 s[98:99], v240, v0
	v_max_f32_e32 v100, v100, v105
	v_cndmask_b32_e64 v104, v101, v236, s[100:101]
	v_cmp_lt_f32_e64 s[100:101], v242, v0
	v_max_f32_e32 v100, v100, v104
	v_cndmask_b32_e32 v105, v101, v238, vcc
	v_cmp_lt_f32_e32 vcc, v251, v0
	v_max_f32_e32 v100, v100, v105
	v_cndmask_b32_e64 v104, v101, v240, s[98:99]
	v_cmp_lt_f32_e64 s[98:99], v253, v0
	v_max_f32_e32 v100, v100, v104
	v_cndmask_b32_e64 v105, v101, v242, s[100:101]
	v_cmp_lt_f32_e64 s[100:101], v133, v0
	v_max_f32_e32 v100, v100, v105
	v_cndmask_b32_e32 v104, v101, v251, vcc
	v_cmp_lt_f32_e32 vcc, v80, v0
	v_max_f32_e32 v100, v100, v104
	v_cndmask_b32_e64 v105, v101, v253, s[98:99]
	v_cmp_lt_f32_e64 s[98:99], v252, v0
	v_max_f32_e32 v100, v100, v105
	v_cndmask_b32_e64 v104, v101, v133, s[100:101]
	v_cmp_lt_f32_e64 s[100:101], v215, v0
	v_max_f32_e32 v100, v100, v104
	v_cndmask_b32_e32 v105, v101, v80, vcc
	v_cmp_lt_f32_e32 vcc, v84, v0
	v_max_f32_e32 v100, v100, v105
	v_cndmask_b32_e64 v104, v101, v252, s[98:99]
	v_cmp_lt_f32_e64 s[98:99], v16, v0
	v_max_f32_e32 v100, v100, v104
	v_cndmask_b32_e64 v105, v101, v215, s[100:101]
	v_max_f32_e32 v100, v100, v105
	v_cndmask_b32_e32 v104, v101, v84, vcc
	v_max_f32_e32 v100, v100, v104
	v_cndmask_b32_e64 v105, v101, v16, s[98:99]
	v_max_f32_e32 v100, v100, v105
	s_nop 1
	v_max_f32_dpp v100, v100, v100 quad_perm:[1,0,3,2] row_mask:0xf bank_mask:0xf
	s_nop 1
	v_max_f32_dpp v100, v100, v100 quad_perm:[2,3,0,1] row_mask:0xf bank_mask:0xf
	s_nop 1
	v_max_f32_dpp v100, v100, v100 row_half_mirror row_mask:0xf bank_mask:0xf
	s_nop 1
	v_max_f32_dpp v100, v100, v100 row_mirror row_mask:0xf bank_mask:0xf
	s_nop 1
	v_max_f32_dpp v100, v100, v100 row_bcast:15 row_mask:0xa bank_mask:0xf
	s_nop 0
	v_readlane_b32 s98, v100, 31
	v_readlane_b32 s99, v100, 63
	s_nop 1
	v_mov_b32_e32 v102, s99
	v_mov_b32_e32 v103, s98
	v_cndmask_b32_e64 v102, v102, v103, s[8:9]
	v_cndmask_b32_e64 v6, v6, v102, s[86:87]
.Lwalk1_u:
	s_cmp_lg_u64 s[88:89], 0
	s_cbranch_scc0 .Lwalk1_e
	v_mov_b32_e32 v100, 0x7f800000
	v_mov_b32_e32 v101, 0x7f800000
	v_cmp_ge_f32_e64 s[98:99], v201, v0
	v_cmp_ge_f32_e64 s[100:101], v209, v0
	v_cmp_ge_f32_e32 vcc, v200, v0
	v_cndmask_b32_e64 v104, v101, v201, s[98:99]
	v_cmp_ge_f32_e64 s[98:99], v202, v0
	v_min_f32_e32 v100, v100, v104
	v_cndmask_b32_e64 v105, v101, v209, s[100:101]
	v_cmp_ge_f32_e64 s[100:101], v112, v0
	v_min_f32_e32 v100, v100, v105
	v_cndmask_b32_e32 v104, v101, v200, vcc
	v_cmp_ge_f32_e32 vcc, v113, v0
	v_min_f32_e32 v100, v100, v104
	v_cndmask_b32_e64 v105, v101, v202, s[98:99]
	v_cmp_ge_f32_e64 s[98:99], v114, v0
	v_min_f32_e32 v100, v100, v105
	v_cndmask_b32_e64 v104, v101, v112, s[100:101]
	v_cmp_ge_f32_e64 s[100:101], v115, v0
	v_min_f32_e32 v100, v100, v104
	v_cndmask_b32_e32 v105, v101, v113, vcc
	v_cmp_ge_f32_e32 vcc, v116, v0
	v_min_f32_e32 v100, v100, v105
	v_cndmask_b32_e64 v104, v101, v114, s[98:99]
	v_cmp_ge_f32_e64 s[98:99], v117, v0
	v_min_f32_e32 v100, v100, v104
	v_cndmask_b32_e64 v105, v101, v115, s[100:101]
	v_cmp_ge_f32_e64 s[100:101], v118, v0
	v_min_f32_e32 v100, v100, v105
	v_cndmask_b32_e32 v104, v101, v116, vcc
	v_cmp_ge_f32_e32 vcc, v119, v0
	v_min_f32_e32 v100, v100, v104
	v_cndmask_b32_e64 v105, v101, v117, s[98:99]
	v_cmp_ge_f32_e64 s[98:99], v205, v0
	v_min_f32_e32 v100, v100, v105
	v_cndmask_b32_e64 v104, v101, v118, s[100:101]
	v_cmp_ge_f32_e64 s[100:101], v206, v0
	v_min_f32_e32 v100, v100, v104
	v_cndmask_b32_e32 v105, v101, v119, vcc
	v_cmp_ge_f32_e32 vcc, v207, v0
	v_min_f32_e32 v100, v100, v105
	v_cndmask_b32_e64 v104, v101, v205, s[98:99]
	v_cmp_ge_f32_e64 s[98:99], v208, v0
	v_min_f32_e32 v100, v100, v104
	v_cndmask_b32_e64 v105, v101, v206, s[100:101]
	v_cmp_ge_f32_e64 s[100:101], v210, v0
	v_min_f32_e32 v100, v100, v105
	v_cndmask_b32_e32 v104, v101, v207, vcc
	v_cmp_ge_f32_e32 vcc, v212, v0
	v_min_f32_e32 v100, v100, v104
	v_cndmask_b32_e64 v105, v101, v208, s[98:99]
	v_cmp_ge_f32_e64 s[98:99], v214, v0
	v_min_f32_e32 v100, v100, v105
	v_cndmask_b32_e64 v104, v101, v210, s[100:101]
	v_cmp_ge_f32_e64 s[100:101], v217, v0
	v_min_f32_e32 v100, v100, v104
	v_cndmask_b32_e32 v105, v101, v212, vcc
	v_cmp_ge_f32_e32 vcc, v211, v0
	v_min_f32_e32 v100, v100, v105
	v_cndmask_b32_e64 v104, v101, v214, s[98:99]
	v_cmp_ge_f32_e64 s[98:99], v213, v0
	v_min_f32_e32 v100, v100, v104
	v_cndmask_b32_e64 v105, v101, v217, s[100:101]
	v_cmp_ge_f32_e64 s[100:101], v216, v0
	v_min_f32_e32 v100, v100, v105
	v_cndmask_b32_e32 v104, v101, v211, vcc
	v_cmp_ge_f32_e32 vcc, v218, v0
	v_min_f32_e32 v100, v100, v104
	v_cndmask_b32_e64 v105, v101, v213, s[98:99]
	v_cmp_ge_f32_e64 s[98:99], v227, v0
	v_min_f32_e32 v100, v100, v105
	v_cndmask_b32_e64 v104, v101, v216, s[100:101]
	v_cmp_ge_f32_e64 s[100:101], v229, v0
	v_min_f32_e32 v100, v100, v104
	v_cndmask_b32_e32 v105, v101, v218, vcc
	v_cmp_ge_f32_e32 vcc, v231, v0
	v_min_f32_e32 v100, v100, v105
	v_cndmask_b32_e64 v104, v101, v227, s[98:99]
	v_cmp_ge_f32_e64 s[98:99], v233, v0
	v_min_f32_e32 v100, v100, v104
	v_cndmask_b32_e64 v105, v101, v229, s[100:101]
	v_cmp_ge_f32_e64 s[100:101], v228, v0
	v_min_f32_e32 v100, v100, v105
	v_cndmask_b32_e32 v104, v101, v231, vcc
	v_cmp_ge_f32_e32 vcc, v230, v0
	v_min_f32_e32 v100, v100, v104
	v_cndmask_b32_e64 v105, v101, v233, s[98:99]
	v_cmp_ge_f32_e64 s[98:99], v232, v0
	v_min_f32_e32 v100, v100, v105
	v_cndmask_b32_e64 v104, v101, v228, s[100:101]
	v_cmp_ge_f32_e64 s[100:101], v234, v0
	v_min_f32_e32 v100, v100, v104
	v_cndmask_b32_e32 v105, v101, v230, vcc
	v_cmp_ge_f32_e32 vcc, v243, v0
	v_min_f32_e32 v100, v100, v105
	v_cndmask_b32_e64 v104, v101, v232, s[98:99]
	v_cmp_ge_f32_e64 s[98:99], v245, v0
	v_min_f32_e32 v100, v100, v104
	v_cndmask_b32_e64 v105, v101, v234, s[100:101]
	v_cmp_ge_f32_e64 s[100:101], v247, v0
	v_min_f32_e32 v100, v100, v105
	v_cndmask_b32_e32 v104, v101, v243, vcc
	v_cmp_ge_f32_e32 vcc, v249, v0
	v_min_f32_e32 v100, v100, v104
	v_cndmask_b32_e64 v105, v101, v245, s[98:99]
	v_cmp_ge_f32_e64 s[98:99], v244, v0
	v_min_f32_e32 v100, v100, v105
	v_cndmask_b32_e64 v104, v101, v247, s[100:101]
	v_cmp_ge_f32_e64 s[100:101], v246, v0
	v_min_f32_e32 v100, v100, v104
	v_cndmask_b32_e32 v105, v101, v249, vcc
	v_cmp_ge_f32_e32 vcc, v248, v0
	v_min_f32_e32 v100, v100, v105
	v_cndmask_b32_e64 v104, v101, v244, s[98:99]
	v_cmp_ge_f32_e64 s[98:99], v250, v0
	v_min_f32_e32 v100, v100, v104
	v_cndmask_b32_e64 v105, v101, v246, s[100:101]
	v_cmp_ge_f32_e64 s[100:101], v219, v0
	v_min_f32_e32 v100, v100, v105
	v_cndmask_b32_e32 v104, v101, v248, vcc
	v_cmp_ge_f32_e32 vcc, v221, v0
	v_min_f32_e32 v100, v100, v104
	v_cndmask_b32_e64 v105, v101, v250, s[98:99]
	v_cmp_ge_f32_e64 s[98:99], v223, v0
	v_min_f32_e32 v100, v100, v105
	v_cndmask_b32_e64 v104, v101, v219, s[100:101]
	v_cmp_ge_f32_e64 s[100:101], v225, v0
	v_min_f32_e32 v100, v100, v104
	v_cndmask_b32_e32 v105, v101, v221, vcc
	v_cmp_ge_f32_e32 vcc, v220, v0
	v_min_f32_e32 v100, v100, v105
	v_cndmask_b32_e64 v104, v101, v223, s[98:99]
	v_cmp_ge_f32_e64 s[98:99], v222, v0
	v_min_f32_e32 v100, v100, v104
	v_cndmask_b32_e64 v105, v101, v225, s[100:101]
	v_cmp_ge_f32_e64 s[100:101], v224, v0
	v_min_f32_e32 v100, v100, v105
	v_cndmask_b32_e32 v104, v101, v220, vcc
	v_cmp_ge_f32_e32 vcc, v226, v0
	v_min_f32_e32 v100, v100, v104
	v_cndmask_b32_e64 v105, v101, v222, s[98:99]
	v_cmp_ge_f32_e64 s[98:99], v235, v0
	v_min_f32_e32 v100, v100, v105
	v_cndmask_b32_e64 v104, v101, v224, s[100:101]
	v_cmp_ge_f32_e64 s[100:101], v237, v0
	v_min_f32_e32 v100, v100, v104
	v_cndmask_b32_e32 v105, v101, v226, vcc
	v_cmp_ge_f32_e32 vcc, v239, v0
	v_min_f32_e32 v100, v100, v105
	v_cndmask_b32_e64 v104, v101, v235, s[98:99]
	v_cmp_ge_f32_e64 s[98:99], v241, v0
	v_min_f32_e32 v100, v100, v104
	v_cndmask_b32_e64 v105, v101, v237, s[100:101]
	v_cmp_ge_f32_e64 s[100:101], v236, v0
	v_min_f32_e32 v100, v100, v105
	v_cndmask_b32_e32 v104, v101, v239, vcc
	v_cmp_ge_f32_e32 vcc, v238, v0
	v_min_f32_e32 v100, v100, v104
	v_cndmask_b32_e64 v105, v101, v241, s[98:99]
	v_cmp_ge_f32_e64 s[98:99], v240, v0
	v_min_f32_e32 v100, v100, v105
	v_cndmask_b32_e64 v104, v101, v236, s[100:101]
	v_cmp_ge_f32_e64 s[100:101], v242, v0
	v_min_f32_e32 v100, v100, v104
	v_cndmask_b32_e32 v105, v101, v238, vcc
	v_cmp_ge_f32_e32 vcc, v251, v0
	v_min_f32_e32 v100, v100, v105
	v_cndmask_b32_e64 v104, v101, v240, s[98:99]
	v_cmp_ge_f32_e64 s[98:99], v253, v0
	v_min_f32_e32 v100, v100, v104
	v_cndmask_b32_e64 v105, v101, v242, s[100:101]
	v_cmp_ge_f32_e64 s[100:101], v133, v0
	v_min_f32_e32 v100, v100, v105
	v_cndmask_b32_e32 v104, v101, v251, vcc
	v_cmp_ge_f32_e32 vcc, v80, v0
	v_min_f32_e32 v100, v100, v104
	v_cndmask_b32_e64 v105, v101, v253, s[98:99]
	v_cmp_ge_f32_e64 s[98:99], v252, v0
	v_min_f32_e32 v100, v100, v105
	v_cndmask_b32_e64 v104, v101, v133, s[100:101]
	v_cmp_ge_f32_e64 s[100:101], v215, v0
	v_min_f32_e32 v100, v100, v104
	v_cndmask_b32_e32 v105, v101, v80, vcc
	v_cmp_ge_f32_e32 vcc, v84, v0
	v_min_f32_e32 v100, v100, v105
	v_cndmask_b32_e64 v104, v101, v252, s[98:99]
	v_cmp_ge_f32_e64 s[98:99], v16, v0
	v_min_f32_e32 v100, v100, v104
	v_cndmask_b32_e64 v105, v101, v215, s[100:101]
	v_min_f32_e32 v100, v100, v105
	v_cndmask_b32_e32 v104, v101, v84, vcc
	v_min_f32_e32 v100, v100, v104
	v_cndmask_b32_e64 v105, v101, v16, s[98:99]
	v_min_f32_e32 v100, v100, v105
	s_nop 1
	v_min_f32_dpp v100, v100, v100 quad_perm:[1,0,3,2] row_mask:0xf bank_mask:0xf
	s_nop 1
	v_min_f32_dpp v100, v100, v100 quad_perm:[2,3,0,1] row_mask:0xf bank_mask:0xf
	s_nop 1
	v_min_f32_dpp v100, v100, v100 row_half_mirror row_mask:0xf bank_mask:0xf
	s_nop 1
	v_min_f32_dpp v100, v100, v100 row_mirror row_mask:0xf bank_mask:0xf
	s_nop 1
	v_min_f32_dpp v100, v100, v100 row_bcast:15 row_mask:0xa bank_mask:0xf
	s_nop 0
	v_readlane_b32 s98, v100, 31
	v_readlane_b32 s99, v100, 63
	s_nop 1
	v_mov_b32_e32 v102, s99
	v_mov_b32_e32 v103, s98
	v_cndmask_b32_e64 v102, v102, v103, s[8:9]
	v_add_f32_e32 v102, 0, v102
	v_ashrrev_i32_e32 v103, 31, v102
	v_or_b32_e32 v103, 1, v103
	v_add_u32_e32 v103, v102, v103
	v_cmp_lg_f32_e32 vcc, 0, v102
	s_and_b64 s[88:89], s[88:89], vcc
	v_cndmask_b32_e64 v6, v6, v103, s[88:89]
.Lwalk1_e:
	s_or_b64 s[82:83], s[86:87], s[88:89]
	s_or_b64 s[74:75], s[74:75], s[82:83]
	s_branch .Lwalkret1
